# GEMM prologues: K-tile 1 staged before the first prologue wait/barrier (vmcnt 2 to 8) so both tile latencies overlap
# speedup vs baseline: 1.0180x; 1.0051x over previous
; #define PG8_STAGE(bufoff, gbase, voff) do { _Pragma("unroll") for (int _i = 0; _i < 2; ++_i) \
;         __builtin_amdgcn_global_load_lds((const unsigned*)((const char*)(gbase) + (voff)[_i]), (PG8_LAS unsigned*)(lds + (bufoff) + ldsw + _i * 8192), 16, 0, 0); } while (0)
; #define PG8_WAIT_V(n) asm volatile("s_waitcnt vmcnt(" #n ")" ::: "memory")
; #define PG8_BAR __builtin_amdgcn_s_barrier()
; template <class Epi, class Sched, bool ALIGN_EPI = false, bool SP2 = false, bool HALFM = false>
; __device__ __forceinline__ void gemm_phase(PG8_LAS unsigned char* lds, const Gemm g, const Sched& S, const Epi& E, const int tid_in) {
;     ...
;     if constexpr (SP2) {
;         PG8_STAGE(PG8_SB(0, 0), cB, voffB); PG8_STAGE(PG8_SB(0, 1), cB + hstep, voffB); PG8_STAGE(PG8_SA(0, 0), cA, voffA); PG8_STAGE(PG8_SA(0, 1), cA + hstep, voffA);
;         if (wr == 1) PG8_BAR;
;         PG8_WAIT_V(2); PG8_BAR;
;         PG8_STAGE(PG8_SB(1, 0), cB + kstep, voffB); PG8_STAGE(PG8_SA(1, 0), cA + kstep, voffA); PG8_STAGE(PG8_SB(1, 1), cB + hstep + kstep, voffB);
;         PG8_WAIT_V(6); PG8_BAR;
.LBB0_56:
	s_sext_i32_i8 s13, s4
	s_add_u32 s4, s90, 0x5801970
	v_bfe_u32 v19, v100, 4, 2
	s_addc_u32 s5, s91, 0
	v_and_b32_e32 v18, 15, v100
	v_lshlrev_b32_e32 v20, 4, v19
	s_add_u32 s8, s90, 0xd800000
	v_lshl_or_b32 v101, s7, 6, v18
	v_lshl_or_b32 v18, v18, 6, v20
	v_lshlrev_b32_e32 v20, 2, v100
	s_addc_u32 s9, s91, 0
	s_lshl_b32 s0, s7, 13
	v_and_b32_e32 v20, 32, v20
	v_bitop3_b32 v21, v18, s0, v20 bitop3:0xde
	s_lshl_b32 s0, s10, 5
	s_and_b32 s7, s0, 0x60
	s_add_i32 m0, s35, 0x18000
	v_lshl_add_u64 v[8:9], v[8:9], 0, s[86:87]
	s_lshl_b32 s0, s7, 7
	global_load_lds_dwordx4 v[8:9], off
	v_lshl_add_u64 v[6:7], v[6:7], 0, s[86:87]
	s_add_i32 m0, s35, 0x1a000
	s_add_i32 s39, s35, 0x8000
	s_add_i32 s40, s35, 0xa000
	v_bitop3_b32 v102, s0, v18, v20 bitop3:0xf6
	global_load_lds_dwordx4 v[6:7], off
	v_lshl_add_u64 v[2:3], v[2:3], 0, s[86:87]
	s_mov_b32 m0, s39
	s_add_u32 s0, s18, 0x60080
	global_load_lds_dwordx4 v[2:3], off
	v_lshl_add_u64 v[2:3], v[4:5], 0, s[86:87]
	s_mov_b32 m0, s40
	s_addc_u32 s1, s19, 0
	global_load_lds_dwordx4 v[2:3], off
	s_add_i32 m0, s35, 0x1c000
	v_lshl_add_u64 v[2:3], s[0:1], 0, v[0:1]
	global_load_lds_dwordx4 v[2:3], off
	v_lshl_add_u64 v[2:3], s[0:1], 0, v[66:67]
	s_add_i32 m0, s35, 0x1e000
	s_cmpk_lt_u32 s6, 0x100
	global_load_lds_dwordx4 v[2:3], off
	s_waitcnt vmcnt(8)
	s_barrier
	s_movk_i32 s6, 0x600
	v_lshl_or_b32 v103, v19, 2, s7
	v_lshrrev_b32_e32 v3, 1, v10
	v_mul_lo_u32 v2, v12, s6
	s_movk_i32 s7, 0x6000
	v_mad_u64_u32 v[2:3], s[0:1], v3, s7, v[2:3]
	v_or_b32_e32 v2, v2, v11
	v_add_lshl_u32 v68, v2, v13, 1
	v_lshrrev_b32_e32 v3, 1, v14
	v_mul_lo_u32 v2, v16, s6
	s_waitcnt vmcnt(6)
	v_mad_u64_u32 v[2:3], s[0:1], v3, s7, v[2:3]
	v_or_b32_e32 v2, v2, v15
	s_cselect_b64 s[10:11], -1, 0
	v_mov_b32_e32 v69, v1
	v_add_lshl_u32 v70, v2, v17, 1
	v_mov_b32_e32 v71, v1
	s_mov_b32 s41, 0
	v_add_u32_e32 v104, 0, v21
	v_mov_b64_e32 v[72:73], s[4:5]
	s_barrier
	s_branch .LBB0_60

; #define PG8_STAGE(bufoff, gbase, voff) do { _Pragma("unroll") for (int _i = 0; _i < 2; ++_i) \
;         __builtin_amdgcn_global_load_lds((const unsigned*)((const char*)(gbase) + (voff)[_i]), (PG8_LAS unsigned*)(lds + (bufoff) + ldsw + _i * 8192), 16, 0, 0); } while (0)
; #define PG8_WAIT_V(n) asm volatile("s_waitcnt vmcnt(" #n ")" ::: "memory")
; #define PG8_BAR __builtin_amdgcn_s_barrier()
; template <class Epi, class Sched, bool ALIGN_EPI = false, bool SP2 = false, bool HALFM = false>
; __device__ __forceinline__ void gemm_phase(PG8_LAS unsigned char* lds, const Gemm g, const Sched& S, const Epi& E, const int tid_in) {
;     ...
;     if constexpr (SP2) {
;         PG8_STAGE(PG8_SB(0, 0), cB, voffB); PG8_STAGE(PG8_SB(0, 1), cB + hstep, voffB); PG8_STAGE(PG8_SA(0, 0), cA, voffA); PG8_STAGE(PG8_SA(0, 1), cA + hstep, voffA);
;         if (wr == 1) PG8_BAR;
;         PG8_WAIT_V(2); PG8_BAR;
;         PG8_STAGE(PG8_SB(1, 0), cB + kstep, voffB); PG8_STAGE(PG8_SA(1, 0), cA + kstep, voffA); PG8_STAGE(PG8_SB(1, 1), cB + hstep + kstep, voffB);
;         PG8_WAIT_V(6); PG8_BAR;
.LBB0_176:
	v_lshl_add_u64 v[2:3], s[8:9], 0, v[0:1]
	v_mov_b32_e32 v137, v1
	v_lshl_add_u64 v[4:5], s[8:9], 0, v[136:137]
	v_mov_b32_e32 v133, v1
	s_add_i32 m0, s77, 0x18000
	v_lshl_add_u64 v[2:3], v[2:3], 0, s[86:87]
	v_lshl_add_u64 v[10:11], s[56:57], 0, v[132:133]
	v_mov_b32_e32 v135, v1
	global_load_lds_dwordx4 v[2:3], off
	v_lshl_add_u64 v[2:3], v[4:5], 0, s[86:87]
	s_add_i32 m0, s77, 0x1a000
	s_add_i32 s61, s77, 0x8000
	v_lshl_add_u64 v[12:13], s[56:57], 0, v[134:135]
	global_load_lds_dwordx4 v[2:3], off
	v_lshl_add_u64 v[2:3], v[10:11], 0, s[86:87]
	s_mov_b32 m0, s61
	s_add_i32 s12, s77, 0xa000
	v_lshl_add_u64 v[6:7], s[4:5], 0, v[0:1]
	global_load_lds_dwordx4 v[2:3], off
	v_lshl_add_u64 v[2:3], v[12:13], 0, s[86:87]
	s_mov_b32 m0, s12
	v_lshl_add_u64 v[8:9], s[4:5], 0, v[136:137]
	global_load_lds_dwordx4 v[2:3], off
	s_add_i32 m0, s77, 0x1c000
	v_lshl_add_u64 v[2:3], v[6:7], 0, s[86:87]
	global_load_lds_dwordx4 v[2:3], off
	v_lshl_add_u64 v[2:3], v[8:9], 0, s[86:87]
	s_add_i32 m0, s77, 0x1e000
	s_lshl_b32 s0, s11, 13
	global_load_lds_dwordx4 v[2:3], off
	s_waitcnt vmcnt(8)
	s_barrier
	v_lshlrev_b32_e32 v3, 2, v146
	v_lshl_or_b32 v2, v146, 6, v154
	v_and_b32_e32 v3, 32, v3
	s_lshr_b32 s18, s59, 6
	v_bitop3_b32 v2, v2, s0, v3 bitop3:0xde
	s_lshl_b32 s0, s7, 5
	s_and_b32 s0, s0, 0x60
	s_add_i32 s13, s18, -2
	s_cmpk_lt_u32 s6, 0x100
	s_cselect_b64 s[50:51], -1, 0
	s_lshl_b32 s19, s58, 3
	v_cvt_f32_ubyte0_e32 v3, s19
	v_rcp_iflag_f32_e32 v3, v3
	v_lshl_or_b32 v157, s0, 7, v155
	v_or_b32_e32 v158, s0, v153
	s_sub_i32 s0, 0, s19
	v_mul_f32_e32 v3, 0x4f7ffffe, v3
	v_cvt_u32_f32_e32 v3, v3
	s_waitcnt vmcnt(6)
	v_lshl_or_b32 v156, s11, 6, v146
	s_mov_b32 s11, s93
	v_readfirstlane_b32 s1, v3
	s_mul_i32 s0, s0, s1
	s_mul_hi_u32 s0, s1, s0
	s_lshl_b32 s20, s58, 2
	s_mov_b32 s21, 0
	s_add_i32 s22, s1, s0
	v_lshl_add_u64 v[138:139], s[92:93], 0, v[132:133]
	v_lshl_add_u64 v[140:141], s[92:93], 0, v[134:135]
	v_add_u32_e32 v159, 0, v2
	s_barrier
	s_branch .LBB0_179

; #define PG8_STAGE(bufoff, gbase, voff) do { _Pragma("unroll") for (int _i = 0; _i < 2; ++_i) \
;         __builtin_amdgcn_global_load_lds((const unsigned*)((const char*)(gbase) + (voff)[_i]), (PG8_LAS unsigned*)(lds + (bufoff) + ldsw + _i * 8192), 16, 0, 0); } while (0)
; #define PG8_WAIT_V(n) asm volatile("s_waitcnt vmcnt(" #n ")" ::: "memory")
; #define PG8_BAR __builtin_amdgcn_s_barrier()
; template <class Epi, class Sched, bool ALIGN_EPI = false, bool SP2 = false, bool HALFM = false>
; __device__ __forceinline__ void gemm_phase(PG8_LAS unsigned char* lds, const Gemm g, const Sched& S, const Epi& E, const int tid_in) {
;     ...
;     if constexpr (SP2) {
;         PG8_STAGE(PG8_SB(0, 0), cB, voffB); PG8_STAGE(PG8_SB(0, 1), cB + hstep, voffB); PG8_STAGE(PG8_SA(0, 0), cA, voffA); PG8_STAGE(PG8_SA(0, 1), cA + hstep, voffA);
;         if (wr == 1) PG8_BAR;
;         PG8_WAIT_V(2); PG8_BAR;
;         PG8_STAGE(PG8_SB(1, 0), cB + kstep, voffB); PG8_STAGE(PG8_SA(1, 0), cA + kstep, voffA); PG8_STAGE(PG8_SB(1, 1), cB + hstep + kstep, voffB);
;         PG8_WAIT_V(6); PG8_BAR;
.LBB0_234:
	v_lshl_add_u64 v[2:3], s[8:9], 0, v[0:1]
	v_mov_b32_e32 v71, v1
	v_lshl_add_u64 v[4:5], s[8:9], 0, v[70:71]
	v_mov_b32_e32 v67, v1
	s_add_i32 m0, s18, 0x18000
	v_lshl_add_u64 v[2:3], v[2:3], 0, s[86:87]
	v_lshl_add_u64 v[10:11], s[10:11], 0, v[66:67]
	v_mov_b32_e32 v69, v1
	global_load_lds_dwordx4 v[2:3], off
	v_lshl_add_u64 v[2:3], v[4:5], 0, s[86:87]
	s_add_i32 m0, s18, 0x1a000
	s_add_i32 s22, s18, 0x8000
	v_lshl_add_u64 v[12:13], s[10:11], 0, v[68:69]
	global_load_lds_dwordx4 v[2:3], off
	v_lshl_add_u64 v[2:3], v[10:11], 0, s[86:87]
	s_mov_b32 m0, s22
	s_add_i32 s23, s18, 0xa000
	v_lshl_add_u64 v[6:7], s[4:5], 0, v[0:1]
	global_load_lds_dwordx4 v[2:3], off
	v_lshl_add_u64 v[2:3], v[12:13], 0, s[86:87]
	s_mov_b32 m0, s23
	v_lshl_add_u64 v[8:9], s[4:5], 0, v[70:71]
	global_load_lds_dwordx4 v[2:3], off
	s_add_i32 m0, s18, 0x1c000
	v_lshl_add_u64 v[2:3], v[6:7], 0, s[86:87]
	global_load_lds_dwordx4 v[2:3], off
	v_lshl_add_u64 v[2:3], v[8:9], 0, s[86:87]
	s_add_i32 m0, s18, 0x1e000
	s_lshl_b32 s0, s29, 13
	global_load_lds_dwordx4 v[2:3], off
	s_waitcnt vmcnt(8)
	s_barrier
	v_lshlrev_b32_e32 v3, 2, v146
	v_lshl_or_b32 v2, v146, 6, v154
	v_and_b32_e32 v3, 32, v3
	s_lshr_b32 s28, s59, 6
	v_bitop3_b32 v2, v2, s0, v3 bitop3:0xde
	s_lshl_b32 s0, s7, 5
	v_lshl_or_b32 v80, s29, 6, v146
	s_and_b32 s0, s0, 0x60
	s_add_i32 s29, s28, -2
	s_cmpk_lt_u32 s6, 0x100
	s_cselect_b64 s[52:53], -1, 0
	s_lshl_b32 s61, s58, 3
	v_cvt_f32_ubyte0_e32 v3, s61
	v_rcp_iflag_f32_e32 v3, v3
	v_lshl_or_b32 v81, s0, 7, v155
	v_or_b32_e32 v82, s0, v153
	s_sub_i32 s0, 0, s61
	v_mul_f32_e32 v3, 0x4f7ffffe, v3
	v_cvt_u32_f32_e32 v3, v3
	s_waitcnt vmcnt(6)
	s_mov_b32 s49, s93
	s_mov_b32 s75, 0
	v_readfirstlane_b32 s1, v3
	s_mul_i32 s0, s0, s1
	s_mul_hi_u32 s0, s1, s0
	s_add_i32 s76, s1, s0
	v_lshl_add_u64 v[72:73], s[92:93], 0, v[66:67]
	v_lshl_add_u64 v[74:75], s[92:93], 0, v[68:69]
	v_add_u32_e32 v83, 0, v2
	s_barrier
	s_branch .LBB0_237

; #define PG8_STAGE(bufoff, gbase, voff) do { _Pragma("unroll") for (int _i = 0; _i < 2; ++_i) \
;         __builtin_amdgcn_global_load_lds((const unsigned*)((const char*)(gbase) + (voff)[_i]), (PG8_LAS unsigned*)(lds + (bufoff) + ldsw + _i * 8192), 16, 0, 0); } while (0)
; #define PG8_WAIT_V(n) asm volatile("s_waitcnt vmcnt(" #n ")" ::: "memory")
; #define PG8_BAR __builtin_amdgcn_s_barrier()
; template <class Epi, class Sched, bool ALIGN_EPI = false, bool SP2 = false, bool HALFM = false>
; __device__ __forceinline__ void gemm_phase(PG8_LAS unsigned char* lds, const Gemm g, const Sched& S, const Epi& E, const int tid_in) {
;     ...
;     if constexpr (SP2) {
;         PG8_STAGE(PG8_SB(0, 0), cB, voffB); PG8_STAGE(PG8_SB(0, 1), cB + hstep, voffB); PG8_STAGE(PG8_SA(0, 0), cA, voffA); PG8_STAGE(PG8_SA(0, 1), cA + hstep, voffA);
;         if (wr == 1) PG8_BAR;
;         PG8_WAIT_V(2); PG8_BAR;
;         PG8_STAGE(PG8_SB(1, 0), cB + kstep, voffB); PG8_STAGE(PG8_SA(1, 0), cA + kstep, voffA); PG8_STAGE(PG8_SB(1, 1), cB + hstep + kstep, voffB);
;         PG8_WAIT_V(6); PG8_BAR;
.LBB0_312:
	s_and_b64 s[0:1], s[4:5], exec
	v_bfe_u32 v12, v130, 4, 2
	v_readlane_b32 s0, v254, 40
	v_and_b32_e32 v11, 15, v130
	v_lshlrev_b32_e32 v13, 4, v12
	v_readlane_b32 s1, v254, 41
	v_lshl_or_b32 v151, s16, 6, v11
	v_lshl_or_b32 v11, v11, 6, v13
	v_lshlrev_b32_e32 v13, 2, v130
	s_sext_i32_i8 s45, s14
	s_waitcnt lgkmcnt(0)
	s_cselect_b32 s15, s1, s9
	s_cselect_b32 s14, s0, s8
	s_lshl_b32 s0, s16, 13
	v_and_b32_e32 v13, 32, v13
	v_bitop3_b32 v14, v11, s0, v13 bitop3:0xde
	s_lshl_b32 s0, s7, 5
	s_and_b32 s4, s0, 0x60
	s_add_i32 m0, s35, 0x18000
	v_lshl_add_u64 v[8:9], v[8:9], 0, s[86:87]
	s_lshl_b32 s0, s4, 7
	global_load_lds_dwordx4 v[8:9], off
	v_lshl_add_u64 v[6:7], v[6:7], 0, s[86:87]
	s_add_i32 m0, s35, 0x1a000
	s_add_i32 s39, s35, 0x8000
	s_add_i32 s40, s35, 0xa000
	v_bitop3_b32 v152, s0, v11, v13 bitop3:0xf6
	global_load_lds_dwordx4 v[6:7], off
	v_lshl_add_u64 v[2:3], v[2:3], 0, s[86:87]
	s_mov_b32 m0, s39
	s_add_u32 s0, s22, 0xb0080
	global_load_lds_dwordx4 v[2:3], off
	v_lshl_add_u64 v[2:3], v[4:5], 0, s[86:87]
	s_mov_b32 m0, s40
	s_addc_u32 s1, s23, 0
	global_load_lds_dwordx4 v[2:3], off
	s_add_i32 m0, s35, 0x1c000
	v_lshl_add_u64 v[2:3], s[0:1], 0, v[0:1]
	global_load_lds_dwordx4 v[2:3], off
	v_lshl_add_u64 v[2:3], s[0:1], 0, v[132:133]
	s_add_i32 m0, s35, 0x1e000
	v_lshl_or_b32 v156, v12, 2, s4
	global_load_lds_dwordx4 v[2:3], off
	s_waitcnt vmcnt(8)
	s_barrier
	s_movk_i32 s4, 0xb00
	v_lshrrev_b32_e32 v3, 1, v131
	v_mul_lo_u32 v2, v142, s4
	s_mov_b32 s5, 0xb000
	v_mad_u64_u32 v[2:3], s[0:1], v3, s5, v[2:3]
	v_or_b32_e32 v2, v2, v145
	s_cmpk_lt_u32 s6, 0x100
	v_add_lshl_u32 v2, v2, v143, 1
	v_mov_b32_e32 v3, v1
	s_mov_b64 s[6:7], 0xb0080
	v_lshl_add_u64 v[134:135], v[2:3], 0, s[6:7]
	v_lshrrev_b32_e32 v3, 1, v10
	v_mul_lo_u32 v2, v147, s4
	v_mad_u64_u32 v[2:3], s[0:1], v3, s5, v[2:3]
	s_waitcnt vmcnt(6)
	v_or_b32_e32 v2, v2, v148
	v_add_lshl_u32 v2, v2, v149, 1
	v_mov_b32_e32 v3, v1
	s_cselect_b64 s[16:17], -1, 0
	v_or_b32_e32 v153, 16, v151
	v_or_b32_e32 v154, 32, v151
	v_or_b32_e32 v155, 48, v151
	v_lshl_add_u64 v[136:137], v[2:3], 0, s[6:7]
	s_mov_b32 s41, 0
	v_add_u32_e32 v157, 0, v14
	s_barrier
	s_branch .LBB0_315

; #define PG8_STAGE(bufoff, gbase, voff) do { _Pragma("unroll") for (int _i = 0; _i < 2; ++_i) \
;         __builtin_amdgcn_global_load_lds((const unsigned*)((const char*)(gbase) + (voff)[_i]), (PG8_LAS unsigned*)(lds + (bufoff) + ldsw + _i * 8192), 16, 0, 0); } while (0)
; #define PG8_WAIT_V(n) asm volatile("s_waitcnt vmcnt(" #n ")" ::: "memory")
; #define PG8_BAR __builtin_amdgcn_s_barrier()
; template <class Epi, class Sched, bool ALIGN_EPI = false, bool SP2 = false, bool HALFM = false>
; __device__ __forceinline__ void gemm_phase(PG8_LAS unsigned char* lds, const Gemm g, const Sched& S, const Epi& E, const int tid_in) {
;     ...
;     if constexpr (SP2) {
;         PG8_STAGE(PG8_SB(0, 0), cB, voffB); PG8_STAGE(PG8_SB(0, 1), cB + hstep, voffB); PG8_STAGE(PG8_SA(0, 0), cA, voffA); PG8_STAGE(PG8_SA(0, 1), cA + hstep, voffA);
;         if (wr == 1) PG8_BAR;
;         PG8_WAIT_V(2); PG8_BAR;
;         PG8_STAGE(PG8_SB(1, 0), cB + kstep, voffB); PG8_STAGE(PG8_SA(1, 0), cA + kstep, voffA); PG8_STAGE(PG8_SB(1, 1), cB + hstep + kstep, voffB);
;         PG8_WAIT_V(6); PG8_BAR;
.LBB0_342:
	v_readlane_b32 s0, v254, 39
	v_bfe_u32 v11, v130, 4, 2
	s_lshl_b32 s0, s0, 25
	v_and_b32_e32 v10, 15, v130
	v_lshlrev_b32_e32 v12, 4, v11
	s_sext_i32_i8 s23, s8
	s_waitcnt lgkmcnt(0)
	s_add_u32 s8, s4, s0
	v_lshl_or_b32 v72, s14, 6, v10
	v_lshl_or_b32 v10, v10, 6, v12
	v_lshlrev_b32_e32 v12, 2, v130
	s_addc_u32 s9, s5, 0
	s_lshl_b32 s0, s14, 13
	v_and_b32_e32 v12, 32, v12
	v_bitop3_b32 v13, v10, s0, v12 bitop3:0xde
	s_lshl_b32 s0, s11, 5
	s_and_b32 s4, s0, 0x60
	s_add_i32 m0, s37, 0x18000
	v_lshl_add_u64 v[8:9], v[8:9], 0, s[86:87]
	s_lshl_b32 s0, s4, 7
	global_load_lds_dwordx4 v[8:9], off
	v_lshl_add_u64 v[6:7], v[6:7], 0, s[86:87]
	s_add_i32 m0, s37, 0x1a000
	s_add_i32 s41, s37, 0x8000
	s_add_i32 s42, s37, 0xa000
	v_bitop3_b32 v73, s0, v10, v12 bitop3:0xf6
	global_load_lds_dwordx4 v[6:7], off
	v_lshl_add_u64 v[2:3], v[2:3], 0, s[86:87]
	s_mov_b32 m0, s41
	s_add_u32 s0, s26, 0x40080
	global_load_lds_dwordx4 v[2:3], off
	v_lshl_add_u64 v[2:3], v[4:5], 0, s[86:87]
	s_mov_b32 m0, s42
	s_addc_u32 s1, s27, 0
	global_load_lds_dwordx4 v[2:3], off
	s_add_i32 m0, s37, 0x1c000
	v_lshl_add_u64 v[2:3], s[0:1], 0, v[0:1]
	global_load_lds_dwordx4 v[2:3], off
	v_lshl_add_u64 v[2:3], s[0:1], 0, v[66:67]
	s_add_i32 m0, s37, 0x1e000
	s_cmpk_lt_u32 s10, 0x100
	global_load_lds_dwordx4 v[2:3], off
	s_waitcnt vmcnt(8)
	s_barrier
	v_lshlrev_b32_e32 v2, 14, v131
	v_and_b32_e32 v2, 0xffff8000, v2
	s_waitcnt vmcnt(6)
	v_lshl_add_u32 v2, v142, 11, v2
	v_and_b32_e32 v3, 1, v131
	v_lshl_or_b32 v2, v3, 6, v2
	s_cselect_b64 s[10:11], -1, 0
	v_or_b32_e32 v74, 16, v72
	v_or_b32_e32 v75, 32, v72
	v_or_b32_e32 v76, 48, v72
	v_lshl_or_b32 v77, v11, 2, s4
	v_lshl_add_u32 v68, v143, 1, v2
	v_mov_b32_e32 v69, v1
	s_mov_b32 s43, 0
	v_add_u32_e32 v78, 0, v13
	s_barrier
	s_branch .LBB0_345

; #define PG8_STAGE(bufoff, gbase, voff) do { _Pragma("unroll") for (int _i = 0; _i < 2; ++_i) \
;         __builtin_amdgcn_global_load_lds((const unsigned*)((const char*)(gbase) + (voff)[_i]), (PG8_LAS unsigned*)(lds + (bufoff) + ldsw + _i * 8192), 16, 0, 0); } while (0)
; #define PG8_WAIT_V(n) asm volatile("s_waitcnt vmcnt(" #n ")" ::: "memory")
; #define PG8_BAR __builtin_amdgcn_s_barrier()
; template <class Epi, class Sched, bool ALIGN_EPI = false, bool SP2 = false, bool HALFM = false>
; __device__ __forceinline__ void gemm_phase(PG8_LAS unsigned char* lds, const Gemm g, const Sched& S, const Epi& E, const int tid_in) {
;     ...
;     if constexpr (SP2) {
;         PG8_STAGE(PG8_SB(0, 0), cB, voffB); PG8_STAGE(PG8_SB(0, 1), cB + hstep, voffB); PG8_STAGE(PG8_SA(0, 0), cA, voffA); PG8_STAGE(PG8_SA(0, 1), cA + hstep, voffA);
;         if (wr == 1) PG8_BAR;
;         PG8_WAIT_V(2); PG8_BAR;
;         PG8_STAGE(PG8_SB(1, 0), cB + kstep, voffB); PG8_STAGE(PG8_SA(1, 0), cA + kstep, voffA); PG8_STAGE(PG8_SB(1, 1), cB + hstep + kstep, voffB);
;         PG8_WAIT_V(6); PG8_BAR;
.LBB0_389:
	v_lshlrev_b32_e32 v11, 2, v151
	v_lshl_add_u64 v[2:3], s[24:25], 0, v[0:1]
	v_mov_b32_e32 v135, v1
	v_lshl_or_b32 v10, v151, 6, v152
	s_lshl_b32 s0, s11, 13
	v_and_b32_e32 v11, 32, v11
	v_lshl_add_u64 v[4:5], s[24:25], 0, v[134:135]
	v_mov_b32_e32 v131, v1
	v_bitop3_b32 v10, v10, s0, v11 bitop3:0xde
	s_lshl_b32 s0, s10, 5
	s_add_i32 m0, s35, 0x18000
	v_lshl_add_u64 v[2:3], v[2:3], 0, s[86:87]
	v_lshl_add_u64 v[6:7], s[22:23], 0, v[130:131]
	v_mov_b32_e32 v133, v1
	s_sext_i32_i16 s21, s4
	s_and_b32 s4, s0, 0x60
	global_load_lds_dwordx4 v[2:3], off
	v_lshl_add_u64 v[2:3], v[4:5], 0, s[86:87]
	s_add_i32 m0, s35, 0x1a000
	s_add_i32 s39, s35, 0x8000
	s_add_i32 s40, s35, 0xa000
	v_lshl_add_u64 v[8:9], s[22:23], 0, v[132:133]
	global_load_lds_dwordx4 v[2:3], off
	v_lshl_add_u64 v[2:3], v[6:7], 0, s[86:87]
	s_mov_b32 m0, s39
	s_add_u32 s0, s24, 0x40080
	global_load_lds_dwordx4 v[2:3], off
	v_lshl_add_u64 v[2:3], v[8:9], 0, s[86:87]
	s_mov_b32 m0, s40
	s_addc_u32 s1, s25, 0
	global_load_lds_dwordx4 v[2:3], off
	s_add_i32 m0, s35, 0x1c000
	v_lshl_add_u64 v[2:3], s[0:1], 0, v[0:1]
	global_load_lds_dwordx4 v[2:3], off
	v_lshl_add_u64 v[2:3], s[0:1], 0, v[134:135]
	s_add_i32 m0, s35, 0x1e000
	s_cmpk_lt_u32 s5, 0x100
	global_load_lds_dwordx4 v[2:3], off
	s_waitcnt vmcnt(8)
	s_barrier
	v_lshlrev_b32_e32 v2, 14, v143
	v_and_b32_e32 v2, 0xffff8000, v2
	v_lshl_add_u32 v2, v144, 11, v2
	v_and_b32_e32 v3, 1, v143
	v_lshl_or_b32 v2, v3, 6, v2
	v_lshl_add_u32 v136, v145, 1, v2
	v_lshlrev_b32_e32 v2, 14, v146
	v_and_b32_e32 v2, 0xffff8000, v2
	s_waitcnt vmcnt(6)
	v_lshl_add_u32 v2, v147, 11, v2
	v_and_b32_e32 v3, 1, v146
	v_lshl_or_b32 v2, v3, 6, v2
	v_lshl_or_b32 v154, s11, 6, v151
	v_lshl_or_b32 v155, s4, 7, v150
	s_cselect_b64 s[10:11], -1, 0
	v_or_b32_e32 v156, s4, v149
	v_mov_b32_e32 v137, v1
	v_lshl_add_u32 v138, v148, 1, v2
	v_mov_b32_e32 v139, v1
	s_mov_b32 s41, 0
	v_add_u32_e32 v157, 0, v10
	s_barrier
	s_branch .LBB0_392

; #define PG8_STAGE(bufoff, gbase, voff) do { _Pragma("unroll") for (int _i = 0; _i < 2; ++_i) \
;         __builtin_amdgcn_global_load_lds((const unsigned*)((const char*)(gbase) + (voff)[_i]), (PG8_LAS unsigned*)(lds + (bufoff) + ldsw + _i * 8192), 16, 0, 0); } while (0)
; #define PG8_WAIT_V(n) asm volatile("s_waitcnt vmcnt(" #n ")" ::: "memory")
; #define PG8_BAR __builtin_amdgcn_s_barrier()
; template <class Epi, class Sched, bool ALIGN_EPI = false, bool SP2 = false, bool HALFM = false>
; __device__ __forceinline__ void gemm_phase(PG8_LAS unsigned char* lds, const Gemm g, const Sched& S, const Epi& E, const int tid_in) {
;     ...
;     if constexpr (SP2) {
;         PG8_STAGE(PG8_SB(0, 0), cB, voffB); PG8_STAGE(PG8_SB(0, 1), cB + hstep, voffB); PG8_STAGE(PG8_SA(0, 0), cA, voffA); PG8_STAGE(PG8_SA(0, 1), cA + hstep, voffA);
;         if (wr == 1) PG8_BAR;
;         PG8_WAIT_V(2); PG8_BAR;
;         PG8_STAGE(PG8_SB(1, 0), cB + kstep, voffB); PG8_STAGE(PG8_SA(1, 0), cA + kstep, voffA); PG8_STAGE(PG8_SB(1, 1), cB + hstep + kstep, voffB);
;         PG8_WAIT_V(6); PG8_BAR;
.LBB0_409:
	v_lshlrev_b32_e32 v11, 2, v151
	v_lshl_or_b32 v10, v151, 6, v152
	s_lshl_b32 s0, s11, 13
	v_and_b32_e32 v11, 32, v11
	v_bitop3_b32 v10, v10, s0, v11 bitop3:0xde
	s_lshl_b32 s0, s5, 5
	s_add_i32 m0, s35, 0x18000
	v_lshl_add_u64 v[8:9], v[8:9], 0, s[86:87]
	s_sext_i32_i8 s21, s4
	s_and_b32 s4, s0, 0x60
	global_load_lds_dwordx4 v[8:9], off
	v_lshl_add_u64 v[6:7], v[6:7], 0, s[86:87]
	s_add_i32 m0, s35, 0x1a000
	s_add_i32 s39, s35, 0x8000
	s_add_i32 s40, s35, 0xa000
	global_load_lds_dwordx4 v[6:7], off
	v_lshl_add_u64 v[2:3], v[2:3], 0, s[86:87]
	s_mov_b32 m0, s39
	s_add_u32 s0, s24, 0x40080
	global_load_lds_dwordx4 v[2:3], off
	v_lshl_add_u64 v[2:3], v[4:5], 0, s[86:87]
	s_mov_b32 m0, s40
	s_addc_u32 s1, s25, 0
	global_load_lds_dwordx4 v[2:3], off
	s_add_i32 m0, s35, 0x1c000
	v_lshl_add_u64 v[2:3], s[0:1], 0, v[0:1]
	global_load_lds_dwordx4 v[2:3], off
	v_lshl_add_u64 v[2:3], s[0:1], 0, v[134:135]
	s_add_i32 m0, s35, 0x1e000
	s_cmpk_lt_u32 s10, 0x100
	global_load_lds_dwordx4 v[2:3], off
	s_waitcnt vmcnt(8)
	s_barrier
	v_or_b32_e32 v2, s4, v149
	v_or_b32_e32 v74, 0xa00, v2
	v_lshlrev_b32_e32 v2, 14, v143
	v_and_b32_e32 v2, 0xffff8000, v2
	v_lshl_add_u32 v2, v144, 11, v2
	v_and_b32_e32 v3, 1, v143
	v_lshl_or_b32 v2, v3, 6, v2
	v_lshl_add_u32 v66, v145, 1, v2
	v_lshlrev_b32_e32 v2, 14, v146
	v_and_b32_e32 v2, 0xffff8000, v2
	s_waitcnt vmcnt(6)
	v_lshl_add_u32 v2, v147, 11, v2
	v_and_b32_e32 v3, 1, v146
	v_lshl_or_b32 v2, v3, 6, v2
	v_lshl_or_b32 v72, s11, 6, v151
	v_lshl_or_b32 v73, s4, 7, v150
	s_cselect_b64 s[10:11], -1, 0
	v_mov_b32_e32 v67, v1
	v_lshl_add_u32 v68, v148, 1, v2
	v_mov_b32_e32 v69, v1
	s_mov_b32 s41, 0
	v_add_u32_e32 v75, 0, v10
	s_barrier
	s_branch .LBB0_412
